# P0 rmsnorm rows software-pipelined with two register sets: next row's 8 loads in flight while current row is reduced and stored
# baseline (speedup 1.0000x reference)
; __device__ __forceinline__ unsigned cvtpk(float lo, float hi) { f32x2 v = {lo, hi}; bf16x2_t b = __builtin_convertvector(v, bf16x2_t); return __builtin_bit_cast(unsigned, b); }
; __global__ void __launch_bounds__(NWAVES * 64, 2) fwd(Args args) {
;     ...
;         for (int m = gw; m < M; m += NGW) {
;             const f32x4* xr = (const f32x4*)(x + (size_t)m * DM) + lane;
;             f32x4 v[8]; float s = 0.f;
; #pragma unroll
;             for (int j = 0; j < 8; ++j) { v[j] = __builtin_nontemporal_load(xr + 64 * j); s += (v[j].x * v[j].x + v[j].y * v[j].y) + (v[j].z * v[j].z + v[j].w * v[j].w); }
;             const float rs = rsqrtf(wave_sum(s) * (1.0f / DM) + EPS);
;             u32x2* o8 = (u32x2*)(U + (size_t)m * DM) + lane;
; #pragma unroll
;             for (int j = 0; j < 8; ++j) { const f32x4 g = ((const f32x4*)attn_norm)[lane + 64 * j]; u32x2 w; w.x = cvtpk(v[j].x * rs * g.x, v[j].y * rs * g.y); w.y = cvtpk(v[j].z * rs * g.z, v[j].w * rs * g.w); o8[64 * j] = w; }
;         }
.LBB0_18:
	v_add_co_u32_e32 v58, vcc, 0xfffff000, v30
	global_load_dwordx4 v[4:7], v[30:31], off offset:-3072 nt
	global_load_dwordx4 v[8:11], v[30:31], off offset:-2048 nt
	global_load_dwordx4 v[0:3], v[30:31], off nt
	v_addc_co_u32_e32 v59, vcc, -1, v31, vcc
	global_load_dwordx4 v[38:41], v[58:59], off offset:-3072 nt
	global_load_dwordx4 v[42:45], v[58:59], off offset:-2048 nt
	global_load_dwordx4 v[46:49], v[58:59], off offset:-1024 nt
	global_load_dwordx4 v[50:53], v[30:31], off offset:-4096 nt
	global_load_dwordx4 v[12:15], v[30:31], off offset:-1024 nt
	s_add_i32 s4, s4, s6
	s_cmpk_gt_i32 s4, 0x1fff
	v_lshl_add_u64 v[30:31], v[30:31], 0, s[16:17]
	s_cbranch_scc1 .Lrm_lastA
.Lrm_loop:
	v_add_co_u32_e32 v58, vcc, 0xfffff000, v30
	global_load_dwordx4 v[132:135], v[30:31], off offset:-3072 nt
	global_load_dwordx4 v[136:139], v[30:31], off offset:-2048 nt
	global_load_dwordx4 v[128:131], v[30:31], off nt
	v_addc_co_u32_e32 v59, vcc, -1, v31, vcc
	global_load_dwordx4 v[144:147], v[58:59], off offset:-3072 nt
	global_load_dwordx4 v[148:151], v[58:59], off offset:-2048 nt
	global_load_dwordx4 v[152:155], v[58:59], off offset:-1024 nt
	global_load_dwordx4 v[156:159], v[30:31], off offset:-4096 nt
	global_load_dwordx4 v[140:143], v[30:31], off offset:-1024 nt
	s_add_i32 s4, s4, s6
	s_cmpk_gt_i32 s4, 0x1fff
	v_lshl_add_u64 v[30:31], v[30:31], 0, s[16:17]
	s_waitcnt vmcnt(12)
	v_mov_b32_e32 v74, v41
	v_pk_mul_f32 v[58:59], v[10:11], v[10:11]
	v_pk_mul_f32 v[60:61], v[8:9], v[8:9]
	v_mul_f32_e32 v70, v2, v2
	s_waitcnt vmcnt(8)
	v_mul_f32_e32 v62, v13, v13
	v_mul_f32_e32 v64, v15, v15
	v_mul_f32_e32 v71, v3, v3
	v_pk_mov_b32 v[66:67], v[60:61], v[58:59] op_sel:[1,0]
	v_mov_b32_e32 v61, v59
	v_pk_fma_f32 v[58:59], v[12:13], v[12:13], v[62:63] op_sel_hi:[1,1,0]
	v_pk_fma_f32 v[62:63], v[14:15], v[14:15], v[64:65] op_sel_hi:[1,1,0]
	v_pk_mul_f32 v[68:69], v[48:49], v[48:49]
	v_pk_add_f32 v[60:61], v[66:67], v[60:61]
	v_pk_mul_f32 v[66:67], v[46:47], v[46:47]
	v_mov_b32_e32 v59, v70
	v_mov_b32_e32 v63, v71
	v_mov_b32_e32 v70, v39
	v_mov_b32_e32 v71, v43
	v_mov_b32_e32 v75, v45
	v_mov_b32_e32 v64, v38
	v_mov_b32_e32 v65, v42
	v_mov_b32_e32 v72, v40
	v_mov_b32_e32 v73, v44
	v_pk_mov_b32 v[80:81], v[66:67], v[68:69] op_sel:[1,0]
	v_mov_b32_e32 v67, v69
	v_pk_add_f32 v[58:59], v[58:59], v[62:63]
	v_pk_mul_f32 v[62:63], v[70:71], v[70:71]
	v_pk_mul_f32 v[68:69], v[74:75], v[74:75]
	v_pk_fma_f32 v[62:63], v[64:65], v[64:65], v[62:63]
	v_pk_fma_f32 v[64:65], v[72:73], v[72:73], v[68:69]
	v_mul_f32_e32 v77, v6, v6
	v_mul_f32_e32 v79, v7, v7
	v_mul_f32_e32 v76, v51, v51
	v_mul_f32_e32 v78, v53, v53
	v_pk_add_f32 v[66:67], v[80:81], v[66:67]
	v_pk_add_f32 v[62:63], v[62:63], v[64:65]
	v_mul_f32_e32 v83, v5, v5
	v_mul_f32_e32 v84, v4, v4
	v_pk_fma_f32 v[70:71], v[50:51], v[50:51], v[76:77] op_sel_hi:[1,1,0]
	v_pk_fma_f32 v[74:75], v[52:53], v[52:53], v[78:79] op_sel_hi:[1,1,0]
	v_pk_add_f32 v[66:67], v[66:67], v[66:67] op_sel:[0,1] op_sel_hi:[1,0]
	v_pk_add_f32 v[62:63], v[62:63], v[62:63] op_sel:[0,1] op_sel_hi:[1,0]
	v_mov_b32_e32 v71, v77
	v_mov_b32_e32 v75, v79
	v_mov_b32_e32 v67, v83
	v_mov_b32_e32 v63, v84
	v_pk_add_f32 v[64:65], v[70:71], v[74:75]
	v_pk_add_f32 v[62:63], v[62:63], v[66:67]
	v_mul_f32_e32 v82, v1, v1
	v_pk_add_f32 v[62:63], v[62:63], v[64:65]
	v_mul_f32_e32 v85, v0, v0
	v_pk_add_f32 v[60:61], v[60:61], v[60:61] op_sel:[0,1] op_sel_hi:[1,0]
	v_pk_add_f32 v[62:63], v[62:63], v[62:63] op_sel:[0,1] op_sel_hi:[1,0]
	v_mov_b32_e32 v61, v82
	v_mov_b32_e32 v63, v85
	v_pk_add_f32 v[60:61], v[62:63], v[60:61]
	s_nop 0
	v_pk_add_f32 v[58:59], v[60:61], v[58:59]
	s_nop 0
	v_add_f32_e32 v58, v58, v59
	ds_bpermute_b32 v59, v32, v58
	s_waitcnt lgkmcnt(0)
	v_add_f32_e32 v58, v58, v59
	ds_bpermute_b32 v59, v33, v58
	s_waitcnt lgkmcnt(0)
	v_add_f32_e32 v58, v58, v59
	ds_bpermute_b32 v59, v34, v58
	s_waitcnt lgkmcnt(0)
	v_add_f32_e32 v58, v58, v59
	ds_bpermute_b32 v59, v35, v58
	s_waitcnt lgkmcnt(0)
	v_add_f32_e32 v58, v58, v59
	ds_bpermute_b32 v59, v36, v58
	s_waitcnt lgkmcnt(0)
	v_add_f32_e32 v58, v58, v59
	ds_bpermute_b32 v59, v37, v58
	s_waitcnt lgkmcnt(0)
	v_add_f32_e32 v58, v58, v59
	v_fmamk_f32 v58, v58, 0x3a000000, v17
	v_mul_f32_e32 v59, 0x4b800000, v58
	v_cmp_gt_f32_e32 vcc, s5, v58
	s_nop 1
	v_cndmask_b32_e32 v58, v58, v59, vcc
	v_rsq_f32_e32 v58, v58
	s_nop 0
	v_mul_f32_e32 v59, 0x45800000, v58
	v_cndmask_b32_e32 v58, v58, v59, vcc
	v_pk_mul_f32 v[38:39], v[58:59], v[38:39] op_sel_hi:[0,1]
	v_pk_mul_f32 v[40:41], v[58:59], v[40:41] op_sel_hi:[0,1]
	v_pk_mul_f32 v[38:39], v[38:39], v[88:89]
	v_pk_mul_f32 v[40:41], v[40:41], v[90:91]
	v_cvt_pk_bf16_f32 v38, v38, v39
	v_cvt_pk_bf16_f32 v39, v40, v41
	global_store_dwordx2 v[28:29], v[38:39], off offset:-3584
	v_pk_mul_f32 v[42:43], v[58:59], v[42:43] op_sel_hi:[0,1]
	v_pk_mul_f32 v[44:45], v[58:59], v[44:45] op_sel_hi:[0,1]
	v_pk_mul_f32 v[42:43], v[42:43], v[92:93]
	v_pk_mul_f32 v[44:45], v[44:45], v[94:95]
	v_cvt_pk_bf16_f32 v42, v42, v43
	v_cvt_pk_bf16_f32 v43, v44, v45
	global_store_dwordx2 v[28:29], v[42:43], off offset:-3072
	v_pk_mul_f32 v[46:47], v[58:59], v[46:47] op_sel_hi:[0,1]
	v_pk_mul_f32 v[48:49], v[58:59], v[48:49] op_sel_hi:[0,1]
	v_pk_mul_f32 v[46:47], v[46:47], v[96:97]
	v_pk_mul_f32 v[48:49], v[48:49], v[98:99]
	v_cvt_pk_bf16_f32 v46, v46, v47
	v_cvt_pk_bf16_f32 v47, v48, v49
	global_store_dwordx2 v[28:29], v[46:47], off offset:-2560
	v_pk_mul_f32 v[50:51], v[58:59], v[50:51] op_sel_hi:[0,1]
	v_pk_mul_f32 v[52:53], v[58:59], v[52:53] op_sel_hi:[0,1]
	v_pk_mul_f32 v[50:51], v[50:51], v[100:101]
	v_pk_mul_f32 v[52:53], v[52:53], v[102:103]
	v_cvt_pk_bf16_f32 v50, v50, v51
; __device__ __forceinline__ unsigned cvtpk(float lo, float hi) { f32x2 v = {lo, hi}; bf16x2_t b = __builtin_convertvector(v, bf16x2_t); return __builtin_bit_cast(unsigned, b); }
; __global__ void __launch_bounds__(NWAVES * 64, 2) fwd(Args args) {
;     ...
;         for (int m = gw; m < M; m += NGW) {
;             const f32x4* xr = (const f32x4*)(x + (size_t)m * DM) + lane;
;             f32x4 v[8]; float s = 0.f;
; #pragma unroll
;             for (int j = 0; j < 8; ++j) { v[j] = __builtin_nontemporal_load(xr + 64 * j); s += (v[j].x * v[j].x + v[j].y * v[j].y) + (v[j].z * v[j].z + v[j].w * v[j].w); }
;             const float rs = rsqrtf(wave_sum(s) * (1.0f / DM) + EPS);
;             u32x2* o8 = (u32x2*)(U + (size_t)m * DM) + lane;
; #pragma unroll
;             for (int j = 0; j < 8; ++j) { const f32x4 g = ((const f32x4*)attn_norm)[lane + 64 * j]; u32x2 w; w.x = cvtpk(v[j].x * rs * g.x, v[j].y * rs * g.y); w.y = cvtpk(v[j].z * rs * g.z, v[j].w * rs * g.w); o8[64 * j] = w; }
;         }
	v_cvt_pk_bf16_f32 v51, v52, v53
	global_store_dwordx2 v[28:29], v[50:51], off offset:-2048
	v_pk_mul_f32 v[4:5], v[58:59], v[4:5] op_sel_hi:[0,1]
	v_pk_mul_f32 v[6:7], v[58:59], v[6:7] op_sel_hi:[0,1]
	v_pk_mul_f32 v[4:5], v[4:5], v[104:105]
	v_pk_mul_f32 v[6:7], v[6:7], v[106:107]
	v_cvt_pk_bf16_f32 v4, v4, v5
	v_cvt_pk_bf16_f32 v5, v6, v7
	global_store_dwordx2 v[28:29], v[4:5], off offset:-1536
	v_pk_mul_f32 v[8:9], v[58:59], v[8:9] op_sel_hi:[0,1]
	v_pk_mul_f32 v[10:11], v[58:59], v[10:11] op_sel_hi:[0,1]
	v_pk_mul_f32 v[8:9], v[8:9], v[108:109]
	v_pk_mul_f32 v[10:11], v[10:11], v[110:111]
	v_cvt_pk_bf16_f32 v8, v8, v9
	v_cvt_pk_bf16_f32 v9, v10, v11
	global_store_dwordx2 v[28:29], v[8:9], off offset:-1024
	v_pk_mul_f32 v[12:13], v[58:59], v[12:13] op_sel_hi:[0,1]
	v_pk_mul_f32 v[14:15], v[58:59], v[14:15] op_sel_hi:[0,1]
	v_pk_mul_f32 v[12:13], v[12:13], v[112:113]
	v_pk_mul_f32 v[14:15], v[14:15], v[114:115]
	v_cvt_pk_bf16_f32 v12, v12, v13
	v_cvt_pk_bf16_f32 v13, v14, v15
	global_store_dwordx2 v[28:29], v[12:13], off offset:-512
	v_pk_mul_f32 v[0:1], v[58:59], v[0:1] op_sel_hi:[0,1]
	v_pk_mul_f32 v[2:3], v[58:59], v[2:3] op_sel_hi:[0,1]
	v_pk_mul_f32 v[0:1], v[0:1], v[116:117]
	v_pk_mul_f32 v[2:3], v[2:3], v[118:119]
	v_cvt_pk_bf16_f32 v0, v0, v1
	v_cvt_pk_bf16_f32 v1, v2, v3
	global_store_dwordx2 v[28:29], v[0:1], off
	v_lshl_add_u64 v[28:29], v[28:29], 0, s[14:15]
	s_cbranch_scc1 .Lrm_lastB
	v_add_co_u32_e32 v58, vcc, 0xfffff000, v30
	global_load_dwordx4 v[4:7], v[30:31], off offset:-3072 nt
	global_load_dwordx4 v[8:11], v[30:31], off offset:-2048 nt
	global_load_dwordx4 v[0:3], v[30:31], off nt
	v_addc_co_u32_e32 v59, vcc, -1, v31, vcc
	global_load_dwordx4 v[38:41], v[58:59], off offset:-3072 nt
	global_load_dwordx4 v[42:45], v[58:59], off offset:-2048 nt
	global_load_dwordx4 v[46:49], v[58:59], off offset:-1024 nt
	global_load_dwordx4 v[50:53], v[30:31], off offset:-4096 nt
	global_load_dwordx4 v[12:15], v[30:31], off offset:-1024 nt
	s_add_i32 s4, s4, s6
	s_cmpk_gt_i32 s4, 0x1fff
	v_lshl_add_u64 v[30:31], v[30:31], 0, s[16:17]
	s_waitcnt vmcnt(12)
	v_mov_b32_e32 v74, v147
	v_pk_mul_f32 v[58:59], v[138:139], v[138:139]
	v_pk_mul_f32 v[60:61], v[136:137], v[136:137]
	v_mul_f32_e32 v70, v130, v130
	s_waitcnt vmcnt(8)
	v_mul_f32_e32 v62, v141, v141
	v_mul_f32_e32 v64, v143, v143
	v_mul_f32_e32 v71, v131, v131
	v_pk_mov_b32 v[66:67], v[60:61], v[58:59] op_sel:[1,0]
	v_mov_b32_e32 v61, v59
	v_pk_fma_f32 v[58:59], v[140:141], v[140:141], v[62:63] op_sel_hi:[1,1,0]
	v_pk_fma_f32 v[62:63], v[142:143], v[142:143], v[64:65] op_sel_hi:[1,1,0]
	v_pk_mul_f32 v[68:69], v[154:155], v[154:155]
	v_pk_add_f32 v[60:61], v[66:67], v[60:61]
	v_pk_mul_f32 v[66:67], v[152:153], v[152:153]
	v_mov_b32_e32 v59, v70
	v_mov_b32_e32 v63, v71
	v_mov_b32_e32 v70, v145
	v_mov_b32_e32 v71, v149
	v_mov_b32_e32 v75, v151
	v_mov_b32_e32 v64, v144
	v_mov_b32_e32 v65, v148
	v_mov_b32_e32 v72, v146
	v_mov_b32_e32 v73, v150
	v_pk_mov_b32 v[80:81], v[66:67], v[68:69] op_sel:[1,0]
	v_mov_b32_e32 v67, v69
	v_pk_add_f32 v[58:59], v[58:59], v[62:63]
	v_pk_mul_f32 v[62:63], v[70:71], v[70:71]
	v_pk_mul_f32 v[68:69], v[74:75], v[74:75]
	v_pk_fma_f32 v[62:63], v[64:65], v[64:65], v[62:63]
	v_pk_fma_f32 v[64:65], v[72:73], v[72:73], v[68:69]
	v_mul_f32_e32 v77, v134, v134
	v_mul_f32_e32 v79, v135, v135
	v_mul_f32_e32 v76, v157, v157
	v_mul_f32_e32 v78, v159, v159
	v_pk_add_f32 v[66:67], v[80:81], v[66:67]
	v_pk_add_f32 v[62:63], v[62:63], v[64:65]
	v_mul_f32_e32 v83, v133, v133
	v_mul_f32_e32 v84, v132, v132
	v_pk_fma_f32 v[70:71], v[156:157], v[156:157], v[76:77] op_sel_hi:[1,1,0]
	v_pk_fma_f32 v[74:75], v[158:159], v[158:159], v[78:79] op_sel_hi:[1,1,0]
	v_pk_add_f32 v[66:67], v[66:67], v[66:67] op_sel:[0,1] op_sel_hi:[1,0]
	v_pk_add_f32 v[62:63], v[62:63], v[62:63] op_sel:[0,1] op_sel_hi:[1,0]
	v_mov_b32_e32 v71, v77
	v_mov_b32_e32 v75, v79
	v_mov_b32_e32 v67, v83
	v_mov_b32_e32 v63, v84
	v_pk_add_f32 v[64:65], v[70:71], v[74:75]
	v_pk_add_f32 v[62:63], v[62:63], v[66:67]
	v_mul_f32_e32 v82, v129, v129
	v_pk_add_f32 v[62:63], v[62:63], v[64:65]
	v_mul_f32_e32 v85, v128, v128
	v_pk_add_f32 v[60:61], v[60:61], v[60:61] op_sel:[0,1] op_sel_hi:[1,0]
	v_pk_add_f32 v[62:63], v[62:63], v[62:63] op_sel:[0,1] op_sel_hi:[1,0]
	v_mov_b32_e32 v61, v82
	v_mov_b32_e32 v63, v85
	v_pk_add_f32 v[60:61], v[62:63], v[60:61]
	s_nop 0
	v_pk_add_f32 v[58:59], v[60:61], v[58:59]
	s_nop 0
	v_add_f32_e32 v58, v58, v59
	ds_bpermute_b32 v59, v32, v58
	s_waitcnt lgkmcnt(0)
	v_add_f32_e32 v58, v58, v59
	ds_bpermute_b32 v59, v33, v58
	s_waitcnt lgkmcnt(0)
	v_add_f32_e32 v58, v58, v59
	ds_bpermute_b32 v59, v34, v58
	s_waitcnt lgkmcnt(0)
	v_add_f32_e32 v58, v58, v59
	ds_bpermute_b32 v59, v35, v58
	s_waitcnt lgkmcnt(0)
	v_add_f32_e32 v58, v58, v59
	ds_bpermute_b32 v59, v36, v58
	s_waitcnt lgkmcnt(0)
	v_add_f32_e32 v58, v58, v59
	ds_bpermute_b32 v59, v37, v58
	s_waitcnt lgkmcnt(0)
; __device__ __forceinline__ unsigned cvtpk(float lo, float hi) { f32x2 v = {lo, hi}; bf16x2_t b = __builtin_convertvector(v, bf16x2_t); return __builtin_bit_cast(unsigned, b); }
; __global__ void __launch_bounds__(NWAVES * 64, 2) fwd(Args args) {
;     ...
;         for (int m = gw; m < M; m += NGW) {
;             const f32x4* xr = (const f32x4*)(x + (size_t)m * DM) + lane;
;             f32x4 v[8]; float s = 0.f;
; #pragma unroll
;             for (int j = 0; j < 8; ++j) { v[j] = __builtin_nontemporal_load(xr + 64 * j); s += (v[j].x * v[j].x + v[j].y * v[j].y) + (v[j].z * v[j].z + v[j].w * v[j].w); }
;             const float rs = rsqrtf(wave_sum(s) * (1.0f / DM) + EPS);
;             u32x2* o8 = (u32x2*)(U + (size_t)m * DM) + lane;
; #pragma unroll
;             for (int j = 0; j < 8; ++j) { const f32x4 g = ((const f32x4*)attn_norm)[lane + 64 * j]; u32x2 w; w.x = cvtpk(v[j].x * rs * g.x, v[j].y * rs * g.y); w.y = cvtpk(v[j].z * rs * g.z, v[j].w * rs * g.w); o8[64 * j] = w; }
;         }
	v_add_f32_e32 v58, v58, v59
	v_fmamk_f32 v58, v58, 0x3a000000, v17
	v_mul_f32_e32 v59, 0x4b800000, v58
	v_cmp_gt_f32_e32 vcc, s5, v58
	s_nop 1
	v_cndmask_b32_e32 v58, v58, v59, vcc
	v_rsq_f32_e32 v58, v58
	s_nop 0
	v_mul_f32_e32 v59, 0x45800000, v58
	v_cndmask_b32_e32 v58, v58, v59, vcc
	v_pk_mul_f32 v[144:145], v[58:59], v[144:145] op_sel_hi:[0,1]
	v_pk_mul_f32 v[146:147], v[58:59], v[146:147] op_sel_hi:[0,1]
	v_pk_mul_f32 v[144:145], v[144:145], v[88:89]
	v_pk_mul_f32 v[146:147], v[146:147], v[90:91]
	v_cvt_pk_bf16_f32 v144, v144, v145
	v_cvt_pk_bf16_f32 v145, v146, v147
	global_store_dwordx2 v[28:29], v[144:145], off offset:-3584
	v_pk_mul_f32 v[148:149], v[58:59], v[148:149] op_sel_hi:[0,1]
	v_pk_mul_f32 v[150:151], v[58:59], v[150:151] op_sel_hi:[0,1]
	v_pk_mul_f32 v[148:149], v[148:149], v[92:93]
	v_pk_mul_f32 v[150:151], v[150:151], v[94:95]
	v_cvt_pk_bf16_f32 v148, v148, v149
	v_cvt_pk_bf16_f32 v149, v150, v151
	global_store_dwordx2 v[28:29], v[148:149], off offset:-3072
	v_pk_mul_f32 v[152:153], v[58:59], v[152:153] op_sel_hi:[0,1]
	v_pk_mul_f32 v[154:155], v[58:59], v[154:155] op_sel_hi:[0,1]
	v_pk_mul_f32 v[152:153], v[152:153], v[96:97]
	v_pk_mul_f32 v[154:155], v[154:155], v[98:99]
	v_cvt_pk_bf16_f32 v152, v152, v153
	v_cvt_pk_bf16_f32 v153, v154, v155
	global_store_dwordx2 v[28:29], v[152:153], off offset:-2560
	v_pk_mul_f32 v[156:157], v[58:59], v[156:157] op_sel_hi:[0,1]
	v_pk_mul_f32 v[158:159], v[58:59], v[158:159] op_sel_hi:[0,1]
	v_pk_mul_f32 v[156:157], v[156:157], v[100:101]
	v_pk_mul_f32 v[158:159], v[158:159], v[102:103]
	v_cvt_pk_bf16_f32 v156, v156, v157
	v_cvt_pk_bf16_f32 v157, v158, v159
	global_store_dwordx2 v[28:29], v[156:157], off offset:-2048
	v_pk_mul_f32 v[132:133], v[58:59], v[132:133] op_sel_hi:[0,1]
	v_pk_mul_f32 v[134:135], v[58:59], v[134:135] op_sel_hi:[0,1]
	v_pk_mul_f32 v[132:133], v[132:133], v[104:105]
	v_pk_mul_f32 v[134:135], v[134:135], v[106:107]
	v_cvt_pk_bf16_f32 v132, v132, v133
	v_cvt_pk_bf16_f32 v133, v134, v135
	global_store_dwordx2 v[28:29], v[132:133], off offset:-1536
	v_pk_mul_f32 v[136:137], v[58:59], v[136:137] op_sel_hi:[0,1]
	v_pk_mul_f32 v[138:139], v[58:59], v[138:139] op_sel_hi:[0,1]
	v_pk_mul_f32 v[136:137], v[136:137], v[108:109]
	v_pk_mul_f32 v[138:139], v[138:139], v[110:111]
	v_cvt_pk_bf16_f32 v136, v136, v137
	v_cvt_pk_bf16_f32 v137, v138, v139
	global_store_dwordx2 v[28:29], v[136:137], off offset:-1024
	v_pk_mul_f32 v[140:141], v[58:59], v[140:141] op_sel_hi:[0,1]
	v_pk_mul_f32 v[142:143], v[58:59], v[142:143] op_sel_hi:[0,1]
	v_pk_mul_f32 v[140:141], v[140:141], v[112:113]
	v_pk_mul_f32 v[142:143], v[142:143], v[114:115]
	v_cvt_pk_bf16_f32 v140, v140, v141
	v_cvt_pk_bf16_f32 v141, v142, v143
	global_store_dwordx2 v[28:29], v[140:141], off offset:-512
	v_pk_mul_f32 v[128:129], v[58:59], v[128:129] op_sel_hi:[0,1]
	v_pk_mul_f32 v[130:131], v[58:59], v[130:131] op_sel_hi:[0,1]
	v_pk_mul_f32 v[128:129], v[128:129], v[116:117]
	v_pk_mul_f32 v[130:131], v[130:131], v[118:119]
	v_cvt_pk_bf16_f32 v128, v128, v129
	v_cvt_pk_bf16_f32 v129, v130, v131
	global_store_dwordx2 v[28:29], v[128:129], off
	v_lshl_add_u64 v[28:29], v[28:29], 0, s[14:15]
	s_cbranch_scc0 .Lrm_loop
.Lrm_lastA:
	s_waitcnt vmcnt(4)
	v_mov_b32_e32 v74, v41
	v_pk_mul_f32 v[58:59], v[10:11], v[10:11]
	v_pk_mul_f32 v[60:61], v[8:9], v[8:9]
	v_mul_f32_e32 v70, v2, v2
	s_waitcnt vmcnt(0)
	v_mul_f32_e32 v62, v13, v13
	v_mul_f32_e32 v64, v15, v15
	v_mul_f32_e32 v71, v3, v3
	v_pk_mov_b32 v[66:67], v[60:61], v[58:59] op_sel:[1,0]
	v_mov_b32_e32 v61, v59
	v_pk_fma_f32 v[58:59], v[12:13], v[12:13], v[62:63] op_sel_hi:[1,1,0]
	v_pk_fma_f32 v[62:63], v[14:15], v[14:15], v[64:65] op_sel_hi:[1,1,0]
	v_pk_mul_f32 v[68:69], v[48:49], v[48:49]
	v_pk_add_f32 v[60:61], v[66:67], v[60:61]
	v_pk_mul_f32 v[66:67], v[46:47], v[46:47]
	v_mov_b32_e32 v59, v70
	v_mov_b32_e32 v63, v71
	v_mov_b32_e32 v70, v39
	v_mov_b32_e32 v71, v43
	v_mov_b32_e32 v75, v45
	v_mov_b32_e32 v64, v38
	v_mov_b32_e32 v65, v42
	v_mov_b32_e32 v72, v40
	v_mov_b32_e32 v73, v44
	v_pk_mov_b32 v[80:81], v[66:67], v[68:69] op_sel:[1,0]
	v_mov_b32_e32 v67, v69
	v_pk_add_f32 v[58:59], v[58:59], v[62:63]
	v_pk_mul_f32 v[62:63], v[70:71], v[70:71]
	v_pk_mul_f32 v[68:69], v[74:75], v[74:75]
	v_pk_fma_f32 v[62:63], v[64:65], v[64:65], v[62:63]
	v_pk_fma_f32 v[64:65], v[72:73], v[72:73], v[68:69]
	v_mul_f32_e32 v77, v6, v6
	v_mul_f32_e32 v79, v7, v7
	v_mul_f32_e32 v76, v51, v51
	v_mul_f32_e32 v78, v53, v53
	v_pk_add_f32 v[66:67], v[80:81], v[66:67]
	v_pk_add_f32 v[62:63], v[62:63], v[64:65]
	v_mul_f32_e32 v83, v5, v5
	v_mul_f32_e32 v84, v4, v4
	v_pk_fma_f32 v[70:71], v[50:51], v[50:51], v[76:77] op_sel_hi:[1,1,0]
	v_pk_fma_f32 v[74:75], v[52:53], v[52:53], v[78:79] op_sel_hi:[1,1,0]
	v_pk_add_f32 v[66:67], v[66:67], v[66:67] op_sel:[0,1] op_sel_hi:[1,0]
	v_pk_add_f32 v[62:63], v[62:63], v[62:63] op_sel:[0,1] op_sel_hi:[1,0]
	v_mov_b32_e32 v71, v77
	v_mov_b32_e32 v75, v79
	v_mov_b32_e32 v67, v83
	v_mov_b32_e32 v63, v84
	v_pk_add_f32 v[64:65], v[70:71], v[74:75]
	v_pk_add_f32 v[62:63], v[62:63], v[66:67]
	v_mul_f32_e32 v82, v1, v1
	v_pk_add_f32 v[62:63], v[62:63], v[64:65]
	v_mul_f32_e32 v85, v0, v0
	v_pk_add_f32 v[60:61], v[60:61], v[60:61] op_sel:[0,1] op_sel_hi:[1,0]
	v_pk_add_f32 v[62:63], v[62:63], v[62:63] op_sel:[0,1] op_sel_hi:[1,0]
	v_mov_b32_e32 v61, v82
	v_mov_b32_e32 v63, v85
	v_pk_add_f32 v[60:61], v[62:63], v[60:61]
	s_nop 0
	v_pk_add_f32 v[58:59], v[60:61], v[58:59]
	s_nop 0
	v_add_f32_e32 v58, v58, v59
	ds_bpermute_b32 v59, v32, v58
	s_waitcnt lgkmcnt(0)
	v_add_f32_e32 v58, v58, v59
	ds_bpermute_b32 v59, v33, v58
	s_waitcnt lgkmcnt(0)
; __device__ __forceinline__ unsigned cvtpk(float lo, float hi) { f32x2 v = {lo, hi}; bf16x2_t b = __builtin_convertvector(v, bf16x2_t); return __builtin_bit_cast(unsigned, b); }
; __global__ void __launch_bounds__(NWAVES * 64, 2) fwd(Args args) {
;     ...
;         for (int m = gw; m < M; m += NGW) {
;             const f32x4* xr = (const f32x4*)(x + (size_t)m * DM) + lane;
;             f32x4 v[8]; float s = 0.f;
; #pragma unroll
;             for (int j = 0; j < 8; ++j) { v[j] = __builtin_nontemporal_load(xr + 64 * j); s += (v[j].x * v[j].x + v[j].y * v[j].y) + (v[j].z * v[j].z + v[j].w * v[j].w); }
;             const float rs = rsqrtf(wave_sum(s) * (1.0f / DM) + EPS);
;             u32x2* o8 = (u32x2*)(U + (size_t)m * DM) + lane;
; #pragma unroll
;             for (int j = 0; j < 8; ++j) { const f32x4 g = ((const f32x4*)attn_norm)[lane + 64 * j]; u32x2 w; w.x = cvtpk(v[j].x * rs * g.x, v[j].y * rs * g.y); w.y = cvtpk(v[j].z * rs * g.z, v[j].w * rs * g.w); o8[64 * j] = w; }
;         }
	v_add_f32_e32 v58, v58, v59
	ds_bpermute_b32 v59, v34, v58
	s_waitcnt lgkmcnt(0)
	v_add_f32_e32 v58, v58, v59
	ds_bpermute_b32 v59, v35, v58
	s_waitcnt lgkmcnt(0)
	v_add_f32_e32 v58, v58, v59
	ds_bpermute_b32 v59, v36, v58
	s_waitcnt lgkmcnt(0)
	v_add_f32_e32 v58, v58, v59
	ds_bpermute_b32 v59, v37, v58
	s_waitcnt lgkmcnt(0)
	v_add_f32_e32 v58, v58, v59
	v_fmamk_f32 v58, v58, 0x3a000000, v17
	v_mul_f32_e32 v59, 0x4b800000, v58
	v_cmp_gt_f32_e32 vcc, s5, v58
	s_nop 1
	v_cndmask_b32_e32 v58, v58, v59, vcc
	v_rsq_f32_e32 v58, v58
	s_nop 0
	v_mul_f32_e32 v59, 0x45800000, v58
	v_cndmask_b32_e32 v58, v58, v59, vcc
	v_pk_mul_f32 v[38:39], v[58:59], v[38:39] op_sel_hi:[0,1]
	v_pk_mul_f32 v[40:41], v[58:59], v[40:41] op_sel_hi:[0,1]
	v_pk_mul_f32 v[38:39], v[38:39], v[88:89]
	v_pk_mul_f32 v[40:41], v[40:41], v[90:91]
	v_cvt_pk_bf16_f32 v38, v38, v39
	v_cvt_pk_bf16_f32 v39, v40, v41
	global_store_dwordx2 v[28:29], v[38:39], off offset:-3584
	v_pk_mul_f32 v[42:43], v[58:59], v[42:43] op_sel_hi:[0,1]
	v_pk_mul_f32 v[44:45], v[58:59], v[44:45] op_sel_hi:[0,1]
	v_pk_mul_f32 v[42:43], v[42:43], v[92:93]
	v_pk_mul_f32 v[44:45], v[44:45], v[94:95]
	v_cvt_pk_bf16_f32 v42, v42, v43
	v_cvt_pk_bf16_f32 v43, v44, v45
	global_store_dwordx2 v[28:29], v[42:43], off offset:-3072
	v_pk_mul_f32 v[46:47], v[58:59], v[46:47] op_sel_hi:[0,1]
	v_pk_mul_f32 v[48:49], v[58:59], v[48:49] op_sel_hi:[0,1]
	v_pk_mul_f32 v[46:47], v[46:47], v[96:97]
	v_pk_mul_f32 v[48:49], v[48:49], v[98:99]
	v_cvt_pk_bf16_f32 v46, v46, v47
	v_cvt_pk_bf16_f32 v47, v48, v49
	global_store_dwordx2 v[28:29], v[46:47], off offset:-2560
	v_pk_mul_f32 v[50:51], v[58:59], v[50:51] op_sel_hi:[0,1]
	v_pk_mul_f32 v[52:53], v[58:59], v[52:53] op_sel_hi:[0,1]
	v_pk_mul_f32 v[50:51], v[50:51], v[100:101]
	v_pk_mul_f32 v[52:53], v[52:53], v[102:103]
	v_cvt_pk_bf16_f32 v50, v50, v51
	v_cvt_pk_bf16_f32 v51, v52, v53
	global_store_dwordx2 v[28:29], v[50:51], off offset:-2048
	v_pk_mul_f32 v[4:5], v[58:59], v[4:5] op_sel_hi:[0,1]
	v_pk_mul_f32 v[6:7], v[58:59], v[6:7] op_sel_hi:[0,1]
	v_pk_mul_f32 v[4:5], v[4:5], v[104:105]
	v_pk_mul_f32 v[6:7], v[6:7], v[106:107]
	v_cvt_pk_bf16_f32 v4, v4, v5
	v_cvt_pk_bf16_f32 v5, v6, v7
	global_store_dwordx2 v[28:29], v[4:5], off offset:-1536
	v_pk_mul_f32 v[8:9], v[58:59], v[8:9] op_sel_hi:[0,1]
	v_pk_mul_f32 v[10:11], v[58:59], v[10:11] op_sel_hi:[0,1]
	v_pk_mul_f32 v[8:9], v[8:9], v[108:109]
	v_pk_mul_f32 v[10:11], v[10:11], v[110:111]
	v_cvt_pk_bf16_f32 v8, v8, v9
	v_cvt_pk_bf16_f32 v9, v10, v11
	global_store_dwordx2 v[28:29], v[8:9], off offset:-1024
	v_pk_mul_f32 v[12:13], v[58:59], v[12:13] op_sel_hi:[0,1]
	v_pk_mul_f32 v[14:15], v[58:59], v[14:15] op_sel_hi:[0,1]
	v_pk_mul_f32 v[12:13], v[12:13], v[112:113]
	v_pk_mul_f32 v[14:15], v[14:15], v[114:115]
	v_cvt_pk_bf16_f32 v12, v12, v13
	v_cvt_pk_bf16_f32 v13, v14, v15
	global_store_dwordx2 v[28:29], v[12:13], off offset:-512
	v_pk_mul_f32 v[0:1], v[58:59], v[0:1] op_sel_hi:[0,1]
	v_pk_mul_f32 v[2:3], v[58:59], v[2:3] op_sel_hi:[0,1]
	v_pk_mul_f32 v[0:1], v[0:1], v[116:117]
	v_pk_mul_f32 v[2:3], v[2:3], v[118:119]
	v_cvt_pk_bf16_f32 v0, v0, v1
	v_cvt_pk_bf16_f32 v1, v2, v3
	global_store_dwordx2 v[28:29], v[0:1], off
	v_lshl_add_u64 v[28:29], v[28:29], 0, s[14:15]
	s_branch .Lrm_done
; __device__ __forceinline__ unsigned cvtpk(float lo, float hi) { f32x2 v = {lo, hi}; bf16x2_t b = __builtin_convertvector(v, bf16x2_t); return __builtin_bit_cast(unsigned, b); }
; __global__ void __launch_bounds__(NWAVES * 64, 2) fwd(Args args) {
;     ...
;         for (int m = gw; m < M; m += NGW) {
;             const f32x4* xr = (const f32x4*)(x + (size_t)m * DM) + lane;
;             f32x4 v[8]; float s = 0.f;
; #pragma unroll
;             for (int j = 0; j < 8; ++j) { v[j] = __builtin_nontemporal_load(xr + 64 * j); s += (v[j].x * v[j].x + v[j].y * v[j].y) + (v[j].z * v[j].z + v[j].w * v[j].w); }
;             const float rs = rsqrtf(wave_sum(s) * (1.0f / DM) + EPS);
;             u32x2* o8 = (u32x2*)(U + (size_t)m * DM) + lane;
; #pragma unroll
;             for (int j = 0; j < 8; ++j) { const f32x4 g = ((const f32x4*)attn_norm)[lane + 64 * j]; u32x2 w; w.x = cvtpk(v[j].x * rs * g.x, v[j].y * rs * g.y); w.y = cvtpk(v[j].z * rs * g.z, v[j].w * rs * g.w); o8[64 * j] = w; }
;         }
;         const int gt = vcu * (NWAVES * 64) + tid, NGT = G * NWAVES * 64;
;         for (int i = gt; i < M * PLE / 8; i += NGT) {
;             const f32x4 a = __builtin_nontemporal_load((const f32x4*)p + 2 * i), b2 = __builtin_nontemporal_load((const f32x4*)p + 2 * i + 1);
;             u32x4 w; w.x = cvtpk(a.x, a.y); w.y = cvtpk(a.z, a.w); w.z = cvtpk(b2.x, b2.y); w.w = cvtpk(b2.z, b2.w);
;             ((u32x4*)PB)[i] = w;
.Lrm_lastB:
	s_waitcnt vmcnt(4)
	v_mov_b32_e32 v74, v147
	v_pk_mul_f32 v[58:59], v[138:139], v[138:139]
	v_pk_mul_f32 v[60:61], v[136:137], v[136:137]
	v_mul_f32_e32 v70, v130, v130
	s_waitcnt vmcnt(0)
	v_mul_f32_e32 v62, v141, v141
	v_mul_f32_e32 v64, v143, v143
	v_mul_f32_e32 v71, v131, v131
	v_pk_mov_b32 v[66:67], v[60:61], v[58:59] op_sel:[1,0]
	v_mov_b32_e32 v61, v59
	v_pk_fma_f32 v[58:59], v[140:141], v[140:141], v[62:63] op_sel_hi:[1,1,0]
	v_pk_fma_f32 v[62:63], v[142:143], v[142:143], v[64:65] op_sel_hi:[1,1,0]
	v_pk_mul_f32 v[68:69], v[154:155], v[154:155]
	v_pk_add_f32 v[60:61], v[66:67], v[60:61]
	v_pk_mul_f32 v[66:67], v[152:153], v[152:153]
	v_mov_b32_e32 v59, v70
	v_mov_b32_e32 v63, v71
	v_mov_b32_e32 v70, v145
	v_mov_b32_e32 v71, v149
	v_mov_b32_e32 v75, v151
	v_mov_b32_e32 v64, v144
	v_mov_b32_e32 v65, v148
	v_mov_b32_e32 v72, v146
	v_mov_b32_e32 v73, v150
	v_pk_mov_b32 v[80:81], v[66:67], v[68:69] op_sel:[1,0]
	v_mov_b32_e32 v67, v69
	v_pk_add_f32 v[58:59], v[58:59], v[62:63]
	v_pk_mul_f32 v[62:63], v[70:71], v[70:71]
	v_pk_mul_f32 v[68:69], v[74:75], v[74:75]
	v_pk_fma_f32 v[62:63], v[64:65], v[64:65], v[62:63]
	v_pk_fma_f32 v[64:65], v[72:73], v[72:73], v[68:69]
	v_mul_f32_e32 v77, v134, v134
	v_mul_f32_e32 v79, v135, v135
	v_mul_f32_e32 v76, v157, v157
	v_mul_f32_e32 v78, v159, v159
	v_pk_add_f32 v[66:67], v[80:81], v[66:67]
	v_pk_add_f32 v[62:63], v[62:63], v[64:65]
	v_mul_f32_e32 v83, v133, v133
	v_mul_f32_e32 v84, v132, v132
	v_pk_fma_f32 v[70:71], v[156:157], v[156:157], v[76:77] op_sel_hi:[1,1,0]
	v_pk_fma_f32 v[74:75], v[158:159], v[158:159], v[78:79] op_sel_hi:[1,1,0]
	v_pk_add_f32 v[66:67], v[66:67], v[66:67] op_sel:[0,1] op_sel_hi:[1,0]
	v_pk_add_f32 v[62:63], v[62:63], v[62:63] op_sel:[0,1] op_sel_hi:[1,0]
	v_mov_b32_e32 v71, v77
	v_mov_b32_e32 v75, v79
	v_mov_b32_e32 v67, v83
	v_mov_b32_e32 v63, v84
	v_pk_add_f32 v[64:65], v[70:71], v[74:75]
	v_pk_add_f32 v[62:63], v[62:63], v[66:67]
	v_mul_f32_e32 v82, v129, v129
	v_pk_add_f32 v[62:63], v[62:63], v[64:65]
	v_mul_f32_e32 v85, v128, v128
	v_pk_add_f32 v[60:61], v[60:61], v[60:61] op_sel:[0,1] op_sel_hi:[1,0]
	v_pk_add_f32 v[62:63], v[62:63], v[62:63] op_sel:[0,1] op_sel_hi:[1,0]
	v_mov_b32_e32 v61, v82
	v_mov_b32_e32 v63, v85
	v_pk_add_f32 v[60:61], v[62:63], v[60:61]
	s_nop 0
	v_pk_add_f32 v[58:59], v[60:61], v[58:59]
	s_nop 0
	v_add_f32_e32 v58, v58, v59
	ds_bpermute_b32 v59, v32, v58
	s_waitcnt lgkmcnt(0)
	v_add_f32_e32 v58, v58, v59
	ds_bpermute_b32 v59, v33, v58
	s_waitcnt lgkmcnt(0)
	v_add_f32_e32 v58, v58, v59
	ds_bpermute_b32 v59, v34, v58
	s_waitcnt lgkmcnt(0)
	v_add_f32_e32 v58, v58, v59
	ds_bpermute_b32 v59, v35, v58
	s_waitcnt lgkmcnt(0)
	v_add_f32_e32 v58, v58, v59
	ds_bpermute_b32 v59, v36, v58
	s_waitcnt lgkmcnt(0)
	v_add_f32_e32 v58, v58, v59
	ds_bpermute_b32 v59, v37, v58
	s_waitcnt lgkmcnt(0)
	v_add_f32_e32 v58, v58, v59
	v_fmamk_f32 v58, v58, 0x3a000000, v17
	v_mul_f32_e32 v59, 0x4b800000, v58
	v_cmp_gt_f32_e32 vcc, s5, v58
	s_nop 1
	v_cndmask_b32_e32 v58, v58, v59, vcc
	v_rsq_f32_e32 v58, v58
	s_nop 0
	v_mul_f32_e32 v59, 0x45800000, v58
	v_cndmask_b32_e32 v58, v58, v59, vcc
	v_pk_mul_f32 v[144:145], v[58:59], v[144:145] op_sel_hi:[0,1]
	v_pk_mul_f32 v[146:147], v[58:59], v[146:147] op_sel_hi:[0,1]
	v_pk_mul_f32 v[144:145], v[144:145], v[88:89]
	v_pk_mul_f32 v[146:147], v[146:147], v[90:91]
	v_cvt_pk_bf16_f32 v144, v144, v145
	v_cvt_pk_bf16_f32 v145, v146, v147
	global_store_dwordx2 v[28:29], v[144:145], off offset:-3584
	v_pk_mul_f32 v[148:149], v[58:59], v[148:149] op_sel_hi:[0,1]
	v_pk_mul_f32 v[150:151], v[58:59], v[150:151] op_sel_hi:[0,1]
	v_pk_mul_f32 v[148:149], v[148:149], v[92:93]
	v_pk_mul_f32 v[150:151], v[150:151], v[94:95]
	v_cvt_pk_bf16_f32 v148, v148, v149
	v_cvt_pk_bf16_f32 v149, v150, v151
	global_store_dwordx2 v[28:29], v[148:149], off offset:-3072
	v_pk_mul_f32 v[152:153], v[58:59], v[152:153] op_sel_hi:[0,1]
	v_pk_mul_f32 v[154:155], v[58:59], v[154:155] op_sel_hi:[0,1]
	v_pk_mul_f32 v[152:153], v[152:153], v[96:97]
	v_pk_mul_f32 v[154:155], v[154:155], v[98:99]
	v_cvt_pk_bf16_f32 v152, v152, v153
	v_cvt_pk_bf16_f32 v153, v154, v155
	global_store_dwordx2 v[28:29], v[152:153], off offset:-2560
	v_pk_mul_f32 v[156:157], v[58:59], v[156:157] op_sel_hi:[0,1]
	v_pk_mul_f32 v[158:159], v[58:59], v[158:159] op_sel_hi:[0,1]
	v_pk_mul_f32 v[156:157], v[156:157], v[100:101]
	v_pk_mul_f32 v[158:159], v[158:159], v[102:103]
	v_cvt_pk_bf16_f32 v156, v156, v157
	v_cvt_pk_bf16_f32 v157, v158, v159
	global_store_dwordx2 v[28:29], v[156:157], off offset:-2048
	v_pk_mul_f32 v[132:133], v[58:59], v[132:133] op_sel_hi:[0,1]
	v_pk_mul_f32 v[134:135], v[58:59], v[134:135] op_sel_hi:[0,1]
	v_pk_mul_f32 v[132:133], v[132:133], v[104:105]
	v_pk_mul_f32 v[134:135], v[134:135], v[106:107]
	v_cvt_pk_bf16_f32 v132, v132, v133
	v_cvt_pk_bf16_f32 v133, v134, v135
	global_store_dwordx2 v[28:29], v[132:133], off offset:-1536
	v_pk_mul_f32 v[136:137], v[58:59], v[136:137] op_sel_hi:[0,1]
	v_pk_mul_f32 v[138:139], v[58:59], v[138:139] op_sel_hi:[0,1]
	v_pk_mul_f32 v[136:137], v[136:137], v[108:109]
	v_pk_mul_f32 v[138:139], v[138:139], v[110:111]
	v_cvt_pk_bf16_f32 v136, v136, v137
	v_cvt_pk_bf16_f32 v137, v138, v139
	global_store_dwordx2 v[28:29], v[136:137], off offset:-1024
	v_pk_mul_f32 v[140:141], v[58:59], v[140:141] op_sel_hi:[0,1]
	v_pk_mul_f32 v[142:143], v[58:59], v[142:143] op_sel_hi:[0,1]
	v_pk_mul_f32 v[140:141], v[140:141], v[112:113]
	v_pk_mul_f32 v[142:143], v[142:143], v[114:115]
	v_cvt_pk_bf16_f32 v140, v140, v141
	v_cvt_pk_bf16_f32 v141, v142, v143
	global_store_dwordx2 v[28:29], v[140:141], off offset:-512
	v_pk_mul_f32 v[128:129], v[58:59], v[128:129] op_sel_hi:[0,1]
	v_pk_mul_f32 v[130:131], v[58:59], v[130:131] op_sel_hi:[0,1]
	v_pk_mul_f32 v[128:129], v[128:129], v[116:117]
	v_pk_mul_f32 v[130:131], v[130:131], v[118:119]
	v_cvt_pk_bf16_f32 v128, v128, v129
	v_cvt_pk_bf16_f32 v129, v130, v131
	global_store_dwordx2 v[28:29], v[128:129], off
	v_lshl_add_u64 v[28:29], v[28:29], 0, s[14:15]
.Lrm_done:
.LBB0_19:
	s_and_b32 s4, s92, 0xffffffc0
	v_add_u32_e32 v0, s4, v16
	v_lshl_add_u32 v2, s95, 9, v0
	s_mov_b32 s4, 0x40000
	s_lshl_b32 s6, s78, 9
	v_cmp_gt_i32_e32 vcc, s4, v2
	s_and_saveexec_b64 s[4:5], vcc
	s_cbranch_execz .LBB0_22
	v_ashrrev_i32_e32 v3, 31, v2
	v_lshl_add_u64 v[4:5], v[2:3], 4, s[80:81]
	s_waitcnt lgkmcnt(0)
	s_mov_b64 s[14:15], 0x4f00000
	s_ashr_i32 s7, s6, 31
	v_lshl_add_u64 v[4:5], v[4:5], 0, s[14:15]
	s_lshl_b64 s[14:15], s[6:7], 4
	v_lshlrev_b32_e32 v6, 1, v2
	s_lshl_b32 s7, s78, 10
	s_mov_b64 s[16:17], 0
	s_mov_b32 s20, 0x3ffff
	v_mov_b32_e32 v1, v2
